# grid barrier: every workgroup writes back L2 before its XCD arrival atomic (amortised release), XCD leader no longer does the single big writeback
# baseline (speedup 1.0000x reference)
; __device__ __forceinline__ unsigned xb_add(unsigned* p, unsigned v) { return __hip_atomic_fetch_add(p, v, __ATOMIC_RELAXED, __HIP_MEMORY_SCOPE_AGENT); }
; __device__ __forceinline__ unsigned xb_xcc_id() { return (unsigned)__builtin_amdgcn_s_getreg((3 << 11) | 20) & 0xFu; }
; __device__ __forceinline__ void xcd_barrier(unsigned* bar, volatile LAS unsigned* st) {
;     ...
;     if (threadIdx.x == 0) {
;         const unsigned x = xb_xcc_id();
;         __builtin_amdgcn_s_waitcnt(0);
;         unsigned nloc = st[0], nx = st[1];
;         if (nloc == 0u) { xcd_barrier_complete(bar, x, nloc, nx); st[0] = nloc; st[1] = nx; }
;         const unsigned old = xb_add(&bar[XB_XSUB(x)], 1u);
;         const unsigned gen = old / nloc;
.LBB0_459:
	s_mov_b64 s[10:11], exec
	s_lshl_b32 s8, s22, 8
	v_mbcnt_lo_u32_b32 v1, s10, 0
	s_add_u32 s8, s6, s8
	v_mbcnt_hi_u32_b32 v1, s11, v1
	s_addc_u32 s9, s7, 0
	v_cmp_eq_u32_e32 vcc, 0, v1
	s_and_saveexec_b64 s[12:13], vcc
	s_cbranch_execz .LBB0_461
	s_bcnt1_i32_b64 s10, s[10:11]
	v_mov_b32_e32 v4, s10
	buffer_wbl2 sc1
	s_waitcnt vmcnt(0)
	global_atomic_add v4, v223, v4, s[8:9] offset:1024 sc0

; __device__ __forceinline__ unsigned xb_add(unsigned* p, unsigned v) { return __hip_atomic_fetch_add(p, v, __ATOMIC_RELAXED, __HIP_MEMORY_SCOPE_AGENT); }
; __device__ __forceinline__ void xcd_barrier(unsigned* bar, volatile LAS unsigned* st) {
;     ...
;         if (old + 1u == (gen + 1u) * nloc) {
;             __builtin_amdgcn_fence(__ATOMIC_RELEASE, "agent");
;             asm volatile("s_waitcnt vmcnt(0)" ::: "memory");
;             const unsigned og = xb_add(&bar[XB_TOP], 1u);
.LBB0_475:
	s_andn2_saveexec_b64 s[10:11], s[10:11]
	s_cbranch_execz .LBB0_495
	s_mov_b64 s[10:11], exec
	s_waitcnt lgkmcnt(0)
	s_waitcnt vmcnt(0)
	v_mbcnt_lo_u32_b32 v1, s10, 0
	v_mbcnt_hi_u32_b32 v1, s11, v1
	v_cmp_eq_u32_e32 vcc, 0, v1
	s_and_saveexec_b64 s[12:13], vcc
	s_cbranch_execz .LBB0_478
	s_bcnt1_i32_b64 s10, s[10:11]
	v_mov_b32_e32 v3, s10
	global_atomic_add v3, v225, v3, s[6:7] offset:1024 sc0

; __device__ __forceinline__ unsigned xb_add(unsigned* p, unsigned v) { return __hip_atomic_fetch_add(p, v, __ATOMIC_RELAXED, __HIP_MEMORY_SCOPE_AGENT); }
; __device__ __forceinline__ void xcd_barrier(unsigned* bar, volatile LAS unsigned* st) {
;     ...
;         if (old + 1u == (gen + 1u) * nloc) {
;             __builtin_amdgcn_fence(__ATOMIC_RELEASE, "agent");
;             asm volatile("s_waitcnt vmcnt(0)" ::: "memory");
;             const unsigned og = xb_add(&bar[XB_TOP], 1u);
.LBB0_1759:
	s_mov_b64 s[10:11], exec
	s_waitcnt lgkmcnt(0)
	s_waitcnt vmcnt(0)
	v_mbcnt_lo_u32_b32 v1, s10, 0
	v_mbcnt_hi_u32_b32 v1, s11, v1
	v_cmp_eq_u32_e32 vcc, 0, v1
	s_and_saveexec_b64 s[12:13], vcc
	s_cbranch_execz .LBB0_1761
	s_bcnt1_i32_b64 s10, s[10:11]
	v_mov_b32_e32 v3, s10
	global_atomic_add v3, v225, v3, s[6:7] offset:1024 sc0
